# v86 + prologue de-serialisation: prep_global B_bar block loads its 16+16 floats with eight 16-byte loads and waits once (was 16 serial load/store round trips per wave)
# baseline (speedup 1.0000x reference)
; __device__ __forceinline__ void prep_global(Frame& F, const Args& a) {
;     ...
;         const double dt = exp((double)a.in[I_LOGDT][l * 32 + g]);
;         const double ar = (double)a.in[I_ARE][i], aim = (double)a.in[I_AIM][i];
;         const double mg = exp(ar * dt * k); double s2, c2; sincos(aim * dt * k, &s2, &c2);
;         float* pw = (float*)(F.ws + WS_SSM + (size_t)l * SO_LAYER + SO_POW) + (size_t)gp * 34;
;         pw[2 * k] = (float)(mg * c2); pw[2 * k + 1] = (float)(mg * s2);
;         if (k == 1) {
.LBB0_34:
	s_or_b64 exec, exec, s[0:1]
	s_waitcnt vmcnt(0)
	v_cvt_f64_f32_e32 v[50:51], v33
	v_mul_f64 v[52:53], v[52:53], v[50:51]
	v_mul_f64 v[52:53], v[52:53], v[54:55]
	v_mul_f64 v[54:55], v[52:53], s[16:17]
	v_rndne_f64_e32 v[54:55], v[54:55]
	v_fma_f64 v[64:65], s[18:19], v[54:55], v[52:53]
	v_fmac_f64_e32 v[64:65], s[20:21], v[54:55]
	v_mov_b64_e32 v[66:67], v[4:5]
	v_fmac_f64_e32 v[66:67], s[22:23], v[64:65]
	v_mov_b64_e32 v[68:69], v[6:7]
	v_fmac_f64_e32 v[68:69], v[64:65], v[66:67]
	v_mov_b64_e32 v[66:67], v[8:9]
	v_fmac_f64_e32 v[66:67], v[64:65], v[68:69]
	v_mov_b64_e32 v[68:69], v[10:11]
	v_fmac_f64_e32 v[68:69], v[64:65], v[66:67]
	v_mov_b64_e32 v[66:67], v[12:13]
	v_fmac_f64_e32 v[66:67], v[64:65], v[68:69]
	v_mov_b64_e32 v[68:69], v[14:15]
	v_fmac_f64_e32 v[68:69], v[64:65], v[66:67]
	v_mov_b64_e32 v[66:67], v[16:17]
	v_fmac_f64_e32 v[66:67], v[64:65], v[68:69]
	v_mov_b64_e32 v[68:69], v[18:19]
	v_fmac_f64_e32 v[68:69], v[64:65], v[66:67]
	v_mov_b64_e32 v[66:67], v[20:21]
	s_mov_b32 s0, 0
	v_fmac_f64_e32 v[66:67], v[64:65], v[68:69]
	s_mov_b32 s1, 0x40900000
	v_fma_f64 v[66:67], v[64:65], v[66:67], 1.0
	v_cmp_nlt_f64_e32 vcc, s[0:1], v[52:53]
	s_mov_b32 s0, 0
	v_fma_f64 v[64:65], v[64:65], v[66:67], 1.0
	v_cvt_i32_f64_e32 v33, v[54:55]
	s_mov_b32 s1, 0xc090cc00
	v_ldexp_f64 v[54:55], v[64:65], v33
	v_cmp_ngt_f64_e64 s[0:1], s[0:1], v[52:53]
	v_cndmask_b32_e32 v33, v1, v55, vcc
	s_and_b64 vcc, s[0:1], vcc
	v_mul_f64 v[52:53], v[56:57], v[56:57]
	v_mov_b64_e32 v[70:71], v[24:25]
	v_cndmask_b32_e32 v64, 0, v54, vcc
	v_mul_f64 v[54:55], v[52:53], 0.5
	v_fmac_f64_e32 v[70:71], s[40:41], v[52:53]
	v_mov_b64_e32 v[72:73], v[26:27]
	v_add_f64 v[66:67], -v[54:55], 1.0
	v_fmac_f64_e32 v[72:73], v[52:53], v[70:71]
	v_mov_b64_e32 v[70:71], v[28:29]
	v_cndmask_b32_e64 v65, 0, v33, s[0:1]
	v_add_f64 v[68:69], -v[66:67], 1.0
	v_fmac_f64_e32 v[70:71], v[52:53], v[72:73]
	v_mov_b64_e32 v[72:73], v[30:31]
	v_mov_b32_e32 v33, v17
	v_add_f64 v[54:55], v[68:69], -v[54:55]
	v_fmac_f64_e32 v[72:73], v[52:53], v[70:71]
	v_mov_b64_e32 v[70:71], v[32:33]
	v_mul_f64 v[68:69], v[52:53], v[52:53]
	v_fmac_f64_e32 v[70:71], v[52:53], v[72:73]
	v_fma_f64 v[54:55], v[56:57], -v[58:59], v[54:55]
	v_fmac_f64_e32 v[54:55], v[68:69], v[70:71]
	v_add_f64 v[54:55], v[66:67], v[54:55]
	v_mov_b64_e32 v[66:67], v[34:35]
	v_fmac_f64_e32 v[66:67], s[44:45], v[52:53]
	v_mov_b64_e32 v[68:69], v[36:37]
	v_fmac_f64_e32 v[68:69], v[52:53], v[66:67]
	v_mov_b64_e32 v[66:67], v[38:39]
	v_mov_b32_e32 v41, v15
	v_fmac_f64_e32 v[66:67], v[52:53], v[68:69]
	v_mov_b64_e32 v[68:69], v[40:41]
	v_fmac_f64_e32 v[68:69], v[52:53], v[66:67]
	v_mul_f64 v[66:67], v[56:57], -v[52:53]
	v_mul_f64 v[70:71], v[58:59], 0.5
	v_fmac_f64_e32 v[70:71], v[66:67], v[68:69]
	v_fma_f64 v[52:53], v[52:53], v[70:71], -v[58:59]
	v_fmac_f64_e32 v[52:53], s[42:43], v[66:67]
	v_and_b32_e32 v41, 1, v47
	v_add_f64 v[52:53], v[56:57], -v[52:53]
	v_cmp_eq_u32_e32 vcc, 0, v41
	v_and_b32_e32 v63, 0x7ff, v42
	v_lshlrev_b32_e32 v33, 30, v47
	v_cndmask_b32_e32 v47, v55, v53, vcc
	v_xor_b32_e32 v53, 0x80000000, v53
	s_movk_i32 s0, 0x1f8
	v_cndmask_b32_e32 v41, v54, v52, vcc
	v_cndmask_b32_e32 v52, v52, v54, vcc
	v_cndmask_b32_e32 v53, v53, v55, vcc
	v_cmp_class_f64_e64 vcc, v[48:49], s0
	v_mul_hi_i32_i24_e32 v55, 0xc0000, v22
	v_mul_i32_i24_e32 v54, 0xc0000, v22
	v_mul_u32_u24_e32 v22, 34, v63
	s_movk_i32 s0, 0xffde
	v_xor_b32_e32 v56, v33, v49
	v_bitop3_b32 v33, v53, v33, s33 bitop3:0x78
	v_cndmask_b32_e32 v48, 0, v52, vcc
	v_lshl_add_u64 v[52:53], s[68:69], 0, v[54:55]
	v_lshlrev_b32_e32 v22, 2, v22
	v_mad_u64_u32 v[58:59], s[0:1], v42, s0, v[2:3]
	v_lshl_add_u64 v[52:53], v[52:53], 0, v[22:23]
	v_ashrrev_i32_e32 v59, 31, v58
	v_bitop3_b32 v47, v47, v56, s33 bitop3:0x78
	v_lshl_add_u64 v[58:59], v[58:59], 2, v[52:53]
	v_cndmask_b32_e32 v49, v62, v33, vcc
	v_cndmask_b32_e32 v56, 0, v41, vcc
	v_cndmask_b32_e32 v57, v62, v47, vcc
	v_add_co_u32_e32 v58, vcc, 0x150000, v58
	v_mul_f64 v[52:53], v[64:65], v[48:49]
	v_mul_f64 v[48:49], v[64:65], v[56:57]
	v_addc_co_u32_e32 v59, vcc, 0, v59, vcc
	v_cvt_f32_f64_e32 v56, v[52:53]
	v_cvt_f32_f64_e32 v57, v[48:49]
	v_cmp_eq_u32_e32 vcc, 1, v46
	global_store_dwordx2 v[58:59], v[56:57], off
	s_and_saveexec_b64 s[46:47], vcc
	s_cbranch_execz .LBB0_29
; __device__ __forceinline__ void prep_global(Frame& F, const Args& a) {
;     ...
;         if (k == 1) {
;             const double lr = mg * c2, li = mg * s2;
;             const double nr = lr - 1.0, ni = li, den = ar * ar + aim * aim;
;             const double cr = (nr * ar + ni * aim) / den, ci = (ni * ar - nr * aim) / den;
;             float* lam = (float*)(F.ws + WS_SSM + (size_t)l * SO_LAYER + SO_LAM); float* bb = (float*)(F.ws + WS_SSM + (size_t)l * SO_LAYER + SO_BBAR);
;             lam[gp * 2] = (float)lr; lam[gp * 2 + 1] = (float)li;
;             const float* bre = a.in[I_BRE] + (size_t)i * 16; const float* bim = a.in[I_BIM] + (size_t)i * 16;
;             for (int h = 0; h < 16; ++h) { const double br = bre[h], bi = bim[h]; bb[(gp * 16 + h) * 2] = (float)(cr * br - ci * bi); bb[(gp * 16 + h) * 2 + 1] = (float)(cr * bi + ci * br); }
	v_lshl_add_u64 v[54:55], s[12:13], 0, v[54:55]
	v_lshlrev_b32_e32 v22, 3, v63
	v_lshl_add_u64 v[46:47], v[54:55], 0, v[22:23]
	v_readlane_b32 s48, v249, 19
	global_store_dwordx2 v[46:47], v[56:57], off
	v_lshlrev_b64 v[46:47], 6, v[42:43]
	v_readlane_b32 s52, v249, 23
	v_readlane_b32 s53, v249, 24
	v_readlane_b32 s54, v249, 25
	v_readlane_b32 s55, v249, 26
	v_lshl_add_u64 v[42:43], s[52:53], 0, v[46:47]
	v_add_f64 v[52:53], v[52:53], -1.0
	v_lshl_add_u64 v[46:47], s[54:55], 0, v[46:47]
	global_load_dwordx4 v[80:83], v[42:43], off
	global_load_dwordx4 v[84:87], v[42:43], off offset:16
	global_load_dwordx4 v[88:91], v[42:43], off offset:32
	global_load_dwordx4 v[92:95], v[42:43], off offset:48
	global_load_dwordx4 v[104:107], v[46:47], off
	global_load_dwordx4 v[108:111], v[46:47], off offset:16
	global_load_dwordx4 v[112:115], v[46:47], off offset:32
	global_load_dwordx4 v[116:119], v[46:47], off offset:48
	v_mul_f64 v[56:57], v[44:45], v[44:45]
	v_mul_f64 v[58:59], v[52:53], v[50:51]
	v_fmac_f64_e32 v[56:57], v[50:51], v[50:51]
	v_mul_f64 v[52:53], v[52:53], v[44:45]
	v_fmac_f64_e32 v[58:59], v[48:49], v[44:45]
	v_lshlrev_b32_e32 v22, 7, v63
	v_fma_f64 v[48:49], v[48:49], v[50:51], -v[52:53]
	v_div_scale_f64 v[44:45], s[0:1], v[56:57], v[56:57], v[58:59]
	v_lshl_add_u64 v[50:51], v[54:55], 0, v[22:23]
	v_div_scale_f64 v[54:55], s[0:1], v[56:57], v[56:57], v[48:49]
	v_rcp_f64_e32 v[66:67], v[44:45]
	v_rcp_f64_e32 v[68:69], v[54:55]
	v_div_scale_f64 v[52:53], vcc, v[58:59], v[56:57], v[58:59]
	v_fma_f64 v[72:73], -v[44:45], v[66:67], 1.0
	v_fma_f64 v[74:75], -v[54:55], v[68:69], 1.0
	v_fmac_f64_e32 v[66:67], v[66:67], v[72:73]
	v_fmac_f64_e32 v[68:69], v[68:69], v[74:75]
	v_fma_f64 v[72:73], -v[44:45], v[66:67], 1.0
	v_fma_f64 v[74:75], -v[54:55], v[68:69], 1.0
	v_fmac_f64_e32 v[66:67], v[66:67], v[72:73]
	v_div_scale_f64 v[64:65], s[0:1], v[48:49], v[56:57], v[48:49]
	v_fmac_f64_e32 v[68:69], v[68:69], v[74:75]
	v_mul_f64 v[72:73], v[52:53], v[66:67]
	v_mul_f64 v[74:75], v[64:65], v[68:69]
	v_fma_f64 v[44:45], -v[44:45], v[72:73], v[52:53]
	v_fma_f64 v[52:53], -v[54:55], v[74:75], v[64:65]
	v_div_fmas_f64 v[44:45], v[44:45], v[66:67], v[72:73]
	s_mov_b64 vcc, s[0:1]
	v_div_fmas_f64 v[52:53], v[52:53], v[68:69], v[74:75]
	v_div_fixup_f64 v[44:45], v[44:45], v[56:57], v[58:59]
	v_div_fixup_f64 v[48:49], v[52:53], v[56:57], v[48:49]
	s_mov_b32 s2, 0x10000
	v_add_co_u32_e64 v70, s[2:3], s2, v50
	s_mov_b64 s[0:1], 0x10000
	s_nop 0
	v_addc_co_u32_e64 v71, s[2:3], 0, v51, s[2:3]
	v_lshl_add_u64 v[50:51], v[50:51], 0, s[0:1]
	v_readlane_b32 s49, v249, 20
	v_readlane_b32 s50, v249, 21
	v_readlane_b32 s51, v249, 22
	v_readlane_b32 s56, v249, 27
	v_readlane_b32 s57, v249, 28
	v_readlane_b32 s58, v249, 29
	v_readlane_b32 s59, v249, 30
	v_readlane_b32 s60, v249, 31
	v_readlane_b32 s61, v249, 32
	v_readlane_b32 s62, v249, 33
	v_readlane_b32 s63, v249, 34
	s_waitcnt vmcnt(0)
; __device__ __forceinline__ void prep_global(Frame& F, const Args& a) {
;     ...
;             const float* bre = a.in[I_BRE] + (size_t)i * 16; const float* bim = a.in[I_BIM] + (size_t)i * 16;
;             for (int h = 0; h < 16; ++h) { const double br = bre[h], bi = bim[h]; bb[(gp * 16 + h) * 2] = (float)(cr * br - ci * bi); bb[(gp * 16 + h) * 2 + 1] = (float)(cr * bi + ci * br); }
	v_cvt_f64_f32_e32 v[52:53], v80
	v_cvt_f64_f32_e32 v[54:55], v104
	v_mul_f64 v[56:57], v[48:49], v[54:55]
	v_mul_f64 v[54:55], v[44:45], v[54:55]
	v_fma_f64 v[56:57], v[44:45], v[52:53], -v[56:57]
	v_fmac_f64_e32 v[54:55], v[48:49], v[52:53]
	v_cvt_f32_f64_e32 v52, v[56:57]
	v_cvt_f32_f64_e32 v53, v[54:55]
	global_store_dwordx2 v[70:71], v[52:53], off
	v_cvt_f64_f32_e32 v[52:53], v81
	v_cvt_f64_f32_e32 v[54:55], v105
	v_mul_f64 v[56:57], v[48:49], v[54:55]
	v_mul_f64 v[54:55], v[44:45], v[54:55]
	v_fma_f64 v[56:57], v[44:45], v[52:53], -v[56:57]
	v_fmac_f64_e32 v[54:55], v[48:49], v[52:53]
	v_cvt_f32_f64_e32 v52, v[56:57]
	v_cvt_f32_f64_e32 v53, v[54:55]
	global_store_dwordx2 v[50:51], v[52:53], off offset:8
	v_cvt_f64_f32_e32 v[52:53], v82
	v_cvt_f64_f32_e32 v[54:55], v106
	v_mul_f64 v[56:57], v[48:49], v[54:55]
	v_mul_f64 v[54:55], v[44:45], v[54:55]
	v_fma_f64 v[56:57], v[44:45], v[52:53], -v[56:57]
	v_fmac_f64_e32 v[54:55], v[48:49], v[52:53]
	v_cvt_f32_f64_e32 v52, v[56:57]
	v_cvt_f32_f64_e32 v53, v[54:55]
	global_store_dwordx2 v[50:51], v[52:53], off offset:16
	v_cvt_f64_f32_e32 v[52:53], v83
	v_cvt_f64_f32_e32 v[54:55], v107
	v_mul_f64 v[56:57], v[48:49], v[54:55]
	v_mul_f64 v[54:55], v[44:45], v[54:55]
	v_fma_f64 v[56:57], v[44:45], v[52:53], -v[56:57]
	v_fmac_f64_e32 v[54:55], v[48:49], v[52:53]
	v_cvt_f32_f64_e32 v52, v[56:57]
	v_cvt_f32_f64_e32 v53, v[54:55]
	global_store_dwordx2 v[50:51], v[52:53], off offset:24
	v_cvt_f64_f32_e32 v[52:53], v84
	v_cvt_f64_f32_e32 v[54:55], v108
	v_mul_f64 v[56:57], v[48:49], v[54:55]
	v_mul_f64 v[54:55], v[44:45], v[54:55]
	v_fma_f64 v[56:57], v[44:45], v[52:53], -v[56:57]
	v_fmac_f64_e32 v[54:55], v[48:49], v[52:53]
	v_cvt_f32_f64_e32 v52, v[56:57]
	v_cvt_f32_f64_e32 v53, v[54:55]
	global_store_dwordx2 v[50:51], v[52:53], off offset:32
	v_cvt_f64_f32_e32 v[52:53], v85
	v_cvt_f64_f32_e32 v[54:55], v109
	v_mul_f64 v[56:57], v[48:49], v[54:55]
	v_mul_f64 v[54:55], v[44:45], v[54:55]
	v_fma_f64 v[56:57], v[44:45], v[52:53], -v[56:57]
	v_fmac_f64_e32 v[54:55], v[48:49], v[52:53]
	v_cvt_f32_f64_e32 v52, v[56:57]
	v_cvt_f32_f64_e32 v53, v[54:55]
	global_store_dwordx2 v[50:51], v[52:53], off offset:40
	v_cvt_f64_f32_e32 v[52:53], v86
	v_cvt_f64_f32_e32 v[54:55], v110
	v_mul_f64 v[56:57], v[48:49], v[54:55]
	v_mul_f64 v[54:55], v[44:45], v[54:55]
	v_fma_f64 v[56:57], v[44:45], v[52:53], -v[56:57]
	v_fmac_f64_e32 v[54:55], v[48:49], v[52:53]
	v_cvt_f32_f64_e32 v52, v[56:57]
	v_cvt_f32_f64_e32 v53, v[54:55]
	global_store_dwordx2 v[50:51], v[52:53], off offset:48
	v_cvt_f64_f32_e32 v[52:53], v87
	v_cvt_f64_f32_e32 v[54:55], v111
	v_mul_f64 v[56:57], v[48:49], v[54:55]
	v_mul_f64 v[54:55], v[44:45], v[54:55]
	v_fma_f64 v[56:57], v[44:45], v[52:53], -v[56:57]
	v_fmac_f64_e32 v[54:55], v[48:49], v[52:53]
	v_cvt_f32_f64_e32 v52, v[56:57]
	v_cvt_f32_f64_e32 v53, v[54:55]
	global_store_dwordx2 v[50:51], v[52:53], off offset:56
	v_cvt_f64_f32_e32 v[52:53], v88
	v_cvt_f64_f32_e32 v[54:55], v112
	v_mul_f64 v[56:57], v[48:49], v[54:55]
	v_mul_f64 v[54:55], v[44:45], v[54:55]
	v_fma_f64 v[56:57], v[44:45], v[52:53], -v[56:57]
	v_fmac_f64_e32 v[54:55], v[48:49], v[52:53]
	v_cvt_f32_f64_e32 v52, v[56:57]
	v_cvt_f32_f64_e32 v53, v[54:55]
	global_store_dwordx2 v[50:51], v[52:53], off offset:64
	v_cvt_f64_f32_e32 v[52:53], v89
	v_cvt_f64_f32_e32 v[54:55], v113
	v_mul_f64 v[56:57], v[48:49], v[54:55]
	v_mul_f64 v[54:55], v[44:45], v[54:55]
	v_fma_f64 v[56:57], v[44:45], v[52:53], -v[56:57]
	v_fmac_f64_e32 v[54:55], v[48:49], v[52:53]
	v_cvt_f32_f64_e32 v52, v[56:57]
	v_cvt_f32_f64_e32 v53, v[54:55]
	global_store_dwordx2 v[50:51], v[52:53], off offset:72
	v_cvt_f64_f32_e32 v[52:53], v90
	v_cvt_f64_f32_e32 v[54:55], v114
	v_mul_f64 v[56:57], v[48:49], v[54:55]
	v_mul_f64 v[54:55], v[44:45], v[54:55]
	v_fma_f64 v[56:57], v[44:45], v[52:53], -v[56:57]
	v_fmac_f64_e32 v[54:55], v[48:49], v[52:53]
	v_cvt_f32_f64_e32 v52, v[56:57]
	v_cvt_f32_f64_e32 v53, v[54:55]
	global_store_dwordx2 v[50:51], v[52:53], off offset:80
	v_cvt_f64_f32_e32 v[52:53], v91
	v_cvt_f64_f32_e32 v[54:55], v115
	v_mul_f64 v[56:57], v[48:49], v[54:55]
	v_mul_f64 v[54:55], v[44:45], v[54:55]
	v_fma_f64 v[56:57], v[44:45], v[52:53], -v[56:57]
	v_fmac_f64_e32 v[54:55], v[48:49], v[52:53]
	v_cvt_f32_f64_e32 v52, v[56:57]
	v_cvt_f32_f64_e32 v53, v[54:55]
	global_store_dwordx2 v[50:51], v[52:53], off offset:88
	v_cvt_f64_f32_e32 v[52:53], v92
	v_cvt_f64_f32_e32 v[54:55], v116
	v_mul_f64 v[56:57], v[48:49], v[54:55]
	v_mul_f64 v[54:55], v[44:45], v[54:55]
	v_fma_f64 v[56:57], v[44:45], v[52:53], -v[56:57]
	v_fmac_f64_e32 v[54:55], v[48:49], v[52:53]
	v_cvt_f32_f64_e32 v52, v[56:57]
	v_cvt_f32_f64_e32 v53, v[54:55]
	global_store_dwordx2 v[50:51], v[52:53], off offset:96
	v_cvt_f64_f32_e32 v[52:53], v93
	v_cvt_f64_f32_e32 v[54:55], v117
	v_mul_f64 v[56:57], v[48:49], v[54:55]
	v_mul_f64 v[54:55], v[44:45], v[54:55]
	v_fma_f64 v[56:57], v[44:45], v[52:53], -v[56:57]
	v_fmac_f64_e32 v[54:55], v[48:49], v[52:53]
	v_cvt_f32_f64_e32 v52, v[56:57]
	v_cvt_f32_f64_e32 v53, v[54:55]
	global_store_dwordx2 v[50:51], v[52:53], off offset:104
	v_cvt_f64_f32_e32 v[52:53], v94
	v_cvt_f64_f32_e32 v[54:55], v118
	v_mul_f64 v[56:57], v[48:49], v[54:55]
	v_mul_f64 v[54:55], v[44:45], v[54:55]
	v_fma_f64 v[56:57], v[44:45], v[52:53], -v[56:57]
	v_fmac_f64_e32 v[54:55], v[48:49], v[52:53]
	v_cvt_f32_f64_e32 v52, v[56:57]
	v_cvt_f32_f64_e32 v53, v[54:55]
	global_store_dwordx2 v[50:51], v[52:53], off offset:112
	v_cvt_f64_f32_e32 v[42:43], v95
	v_cvt_f64_f32_e32 v[46:47], v119
	v_mul_f64 v[52:53], v[48:49], v[46:47]
	v_mul_f64 v[46:47], v[44:45], v[46:47]
	v_fma_f64 v[44:45], v[44:45], v[42:43], -v[52:53]
	v_fmac_f64_e32 v[46:47], v[48:49], v[42:43]
	v_cvt_f32_f64_e32 v42, v[44:45]
	v_cvt_f32_f64_e32 v43, v[46:47]
	global_store_dwordx2 v[50:51], v[42:43], off offset:120
	s_branch .LBB0_29

; #define PG8_WAIT_V(n) asm volatile("s_waitcnt vmcnt(" #n ")" ::: "memory")
; template <class Epi, bool ALIGN_EPI, bool SP2, class Hook>
; __device__ __forceinline__ void gemm_phase(LAS unsigned char* lds, const Gemm g, const StaticOrder& S, const Epi& E, Acc& acc, const bool fresh, const Hook& H, const int wave_id) {
;     ...
;         if constexpr (SP2 && Epi::NSTORE > 0) {
;             const Src a1 = cA + kstep, a2 = cA + 2 * kstep, b2 = cB + 2 * kstep, a3 = a2 + kstep, b3 = b2 + kstep;
;             if constexpr (Epi::NSTORE == 16) PG8_TRIP_SP2(PG8_WAIT_V(24)); else PG8_TRIP_SP2(PG8_WAIT_V(16));
.LBB0_382:
	ds_read_b128 v[2:5], v150
	ds_read_b128 v[6:9], v150 offset:1024
	ds_read_b128 v[10:13], v150 offset:2048
	ds_read_b128 v[14:17], v150 offset:3072
	ds_read_b128 v[18:21], v151
	ds_read_b128 v[22:25], v151 offset:1024
	ds_read_b128 v[26:29], v151 offset:2048
	ds_read_b128 v[30:33], v151 offset:3072
	s_or_b32 s9, s68, 0x100
	s_or_b32 s8, s68, 0x180
	s_or_b32 s10, s69, 0x100
	s_or_b32 s11, s68, 0x40080
	s_mov_b32 m0, s45
	ds_read_b128 v[34:37], v149
	ds_read_b128 v[38:41], v149 offset:1024
	ds_read_b128 v[42:45], v149 offset:2048
	ds_read_b128 v[46:49], v149 offset:3072
	ds_read_b128 v[50:53], v149 offset:4096
	ds_read_b128 v[54:57], v149 offset:5120
	ds_read_b128 v[58:61], v149 offset:6144
	ds_read_b128 v[62:65], v149 offset:7168
	buffer_load_dwordx4 v144, s[0:3], s11 offen lds
	s_mov_b32 m0, s46
	s_nop 0
	buffer_load_dwordx4 v146, s[0:3], s11 offen lds
	s_waitcnt vmcnt(24)
	s_waitcnt lgkmcnt(0)
	s_nop 0
	s_setprio 1
	s_barrier
	v_mfma_f32_16x16x32_bf16 v[86:89], v[10:13], v[50:53], 0
	v_mfma_f32_16x16x32_bf16 v[92:95], v[14:17], v[54:57], v[86:89]
	v_mfma_f32_16x16x32_bf16 v[86:89], v[2:5], v[58:61], 0
	v_mfma_f32_16x16x32_bf16 v[66:69], v[2:5], v[34:37], 0
	v_mfma_f32_16x16x32_bf16 v[70:73], v[10:13], v[34:37], 0
	v_mfma_f32_16x16x32_bf16 v[74:77], v[2:5], v[42:45], 0
	v_mfma_f32_16x16x32_bf16 v[78:81], v[10:13], v[42:45], 0
	v_mfma_f32_16x16x32_bf16 v[82:85], v[2:5], v[50:53], 0
	v_mfma_f32_16x16x32_bf16 v[96:99], v[6:9], v[62:65], v[86:89]
	v_mfma_f32_16x16x32_bf16 v[86:89], v[10:13], v[58:61], 0
	v_mfma_f32_16x16x32_bf16 v[66:69], v[6:9], v[38:41], v[66:69]
	v_mfma_f32_16x16x32_bf16 v[70:73], v[14:17], v[38:41], v[70:73]
	v_mfma_f32_16x16x32_bf16 v[74:77], v[6:9], v[46:49], v[74:77]
	v_mfma_f32_16x16x32_bf16 v[78:81], v[14:17], v[46:49], v[78:81]
	v_mfma_f32_16x16x32_bf16 v[82:85], v[6:9], v[54:57], v[82:85]
	v_mfma_f32_16x16x32_bf16 v[104:107], v[14:17], v[62:65], v[86:89]
	v_mfma_f32_16x16x32_bf16 v[86:89], v[18:21], v[34:37], 0
	v_mfma_f32_16x16x32_bf16 v[34:37], v[26:29], v[34:37], 0
	v_mfma_f32_16x16x32_bf16 v[116:119], v[30:33], v[38:41], v[34:37]
	v_mfma_f32_16x16x32_bf16 v[34:37], v[18:21], v[42:45], 0
	v_mfma_f32_16x16x32_bf16 v[132:135], v[22:25], v[46:49], v[34:37]
	v_mfma_f32_16x16x32_bf16 v[34:37], v[26:29], v[42:45], 0
	v_mfma_f32_16x16x32_bf16 v[108:111], v[22:25], v[38:41], v[86:89]
	v_mfma_f32_16x16x32_bf16 v[40:43], v[30:33], v[46:49], v[34:37]
	v_mfma_f32_16x16x32_bf16 v[34:37], v[18:21], v[50:53], 0
	v_mfma_f32_16x16x32_bf16 v[44:47], v[22:25], v[54:57], v[34:37]
	v_mfma_f32_16x16x32_bf16 v[34:37], v[26:29], v[50:53], 0
	v_mfma_f32_16x16x32_bf16 v[48:51], v[30:33], v[54:57], v[34:37]
	v_mfma_f32_16x16x32_bf16 v[34:37], v[18:21], v[58:61], 0
	v_mfma_f32_16x16x32_bf16 v[52:55], v[22:25], v[62:65], v[34:37]
	v_mfma_f32_16x16x32_bf16 v[34:37], v[26:29], v[58:61], 0
	v_mfma_f32_16x16x32_bf16 v[60:63], v[30:33], v[62:65], v[34:37]
	s_barrier
	s_setprio 0
	s_mov_b32 m0, s92
	s_nop 3
	ds_read_b128 v[34:37], v149 offset:16384
	ds_read_b128 v[56:59], v149 offset:17408
	ds_read_b128 v[86:89], v149 offset:18432
	ds_read_b128 v[100:103], v149 offset:19456
	ds_read_b128 v[112:115], v149 offset:20480
	ds_read_b128 v[120:123], v149 offset:21504
	ds_read_b128 v[124:127], v149 offset:22528
	ds_read_b128 v[128:131], v149 offset:23552
	buffer_load_dwordx4 v145, s[4:7], s10 offen lds
	s_mov_b32 m0, s93
	s_nop 0
	buffer_load_dwordx4 v147, s[4:7], s10 offen lds
	s_or_b32 s10, s69, 0x40100
	s_mov_b32 m0, s94
	s_nop 0
	buffer_load_dwordx4 v145, s[4:7], s10 offen lds
	s_mov_b32 m0, s95
	s_nop 0
	buffer_load_dwordx4 v147, s[4:7], s10 offen lds
	s_waitcnt vmcnt(22)
	s_waitcnt lgkmcnt(0)
	s_setprio 1
	s_barrier
	v_mfma_f32_16x16x32_bf16 v[136:139], v[2:5], v[34:37], 0
	v_mfma_f32_16x16x32_bf16 v[154:157], v[2:5], v[86:89], 0
	v_mfma_f32_16x16x32_bf16 v[162:165], v[2:5], v[112:115], 0
	v_mfma_f32_16x16x32_bf16 v[2:5], v[2:5], v[124:127], 0
	v_mfma_f32_16x16x32_bf16 v[136:139], v[6:9], v[56:59], v[136:139]
	v_mfma_f32_16x16x32_bf16 v[140:143], v[10:13], v[34:37], 0
	v_mfma_f32_16x16x32_bf16 v[154:157], v[6:9], v[100:103], v[154:157]
	v_mfma_f32_16x16x32_bf16 v[158:161], v[10:13], v[86:89], 0
	v_mfma_f32_16x16x32_bf16 v[162:165], v[6:9], v[120:123], v[162:165]
	v_mfma_f32_16x16x32_bf16 v[166:169], v[10:13], v[112:115], 0
	v_mfma_f32_16x16x32_bf16 v[2:5], v[6:9], v[128:131], v[2:5]
	v_mfma_f32_16x16x32_bf16 v[6:9], v[10:13], v[124:127], 0
	v_mfma_f32_16x16x32_bf16 v[140:143], v[14:17], v[56:59], v[140:143]
	v_mfma_f32_16x16x32_bf16 v[158:161], v[14:17], v[100:103], v[158:161]
	v_mfma_f32_16x16x32_bf16 v[166:169], v[14:17], v[120:123], v[166:169]
	v_mfma_f32_16x16x32_bf16 v[170:173], v[14:17], v[128:131], v[6:9]
	v_mfma_f32_16x16x32_bf16 v[6:9], v[18:21], v[34:37], 0
	v_mfma_f32_16x16x32_bf16 v[174:177], v[22:25], v[56:59], v[6:9]
	v_mfma_f32_16x16x32_bf16 v[6:9], v[26:29], v[34:37], 0
	v_mfma_f32_16x16x32_bf16 v[178:181], v[30:33], v[56:59], v[6:9]
	v_mfma_f32_16x16x32_bf16 v[6:9], v[18:21], v[86:89], 0
	v_mfma_f32_16x16x32_bf16 v[182:185], v[22:25], v[100:103], v[6:9]
	v_mfma_f32_16x16x32_bf16 v[6:9], v[26:29], v[86:89], 0
	v_mfma_f32_16x16x32_bf16 v[186:189], v[30:33], v[100:103], v[6:9]
	v_mfma_f32_16x16x32_bf16 v[6:9], v[18:21], v[112:115], 0
	v_mfma_f32_16x16x32_bf16 v[190:193], v[22:25], v[120:123], v[6:9]
	v_mfma_f32_16x16x32_bf16 v[6:9], v[26:29], v[112:115], 0
	v_mfma_f32_16x16x32_bf16 v[212:215], v[30:33], v[120:123], v[6:9]
	v_mfma_f32_16x16x32_bf16 v[6:9], v[18:21], v[124:127], 0
	v_mfma_f32_16x16x32_bf16 v[20:23], v[22:25], v[128:131], v[6:9]
	v_mfma_f32_16x16x32_bf16 v[6:9], v[26:29], v[124:127], 0
	v_mfma_f32_16x16x32_bf16 v[216:219], v[30:33], v[128:131], v[6:9]
	s_barrier
; #define PG8_WAIT_V(n) asm volatile("s_waitcnt vmcnt(" #n ")" ::: "memory")
; template <class Epi, bool ALIGN_EPI, bool SP2, class Hook>
; __device__ __forceinline__ void gemm_phase(LAS unsigned char* lds, const Gemm g, const StaticOrder& S, const Epi& E, Acc& acc, const bool fresh, const Hook& H, const int wave_id) {
;     ...
;         if constexpr (SP2 && Epi::NSTORE > 0) {
;             const Src a1 = cA + kstep, a2 = cA + 2 * kstep, b2 = cB + 2 * kstep, a3 = a2 + kstep, b3 = b2 + kstep;
;             if constexpr (Epi::NSTORE == 16) PG8_TRIP_SP2(PG8_WAIT_V(24)); else PG8_TRIP_SP2(PG8_WAIT_V(16));
	s_setprio 0
	s_mov_b32 m0, s44
	s_nop 0
	buffer_load_dwordx4 v144, s[0:3], s9 offen lds
	s_mov_b32 m0, s36
	s_nop 0
	buffer_load_dwordx4 v146, s[0:3], s9 offen lds
	s_nop 4
	ds_read_b128 v[6:9], v152
	ds_read_b128 v[24:27], v152 offset:1024
	ds_read_b128 v[228:231], v152 offset:2048
	ds_read_b128 v[232:235], v152 offset:3072
	ds_read_b128 v[236:239], v153
	ds_read_b128 v[240:243], v153 offset:1024
	ds_read_b128 v[244:247], v153 offset:2048
	ds_read_b128 v[150:153], v153 offset:3072
	s_or_b32 s9, s68, 0x40100
	s_mov_b32 m0, s37
	ds_read_b128 v[10:13], v149 offset:32768
	ds_read_b128 v[14:17], v149 offset:33792
	ds_read_b128 v[32:35], v149 offset:34816
	ds_read_b128 v[194:197], v149 offset:35840
	ds_read_b128 v[208:211], v149 offset:36864
	ds_read_b128 v[200:203], v149 offset:37888
	ds_read_b128 v[204:207], v149 offset:38912
	ds_read_b128 v[220:223], v149 offset:39936
	buffer_load_dwordx4 v144, s[0:3], s9 offen lds
	s_mov_b32 m0, s38
	s_nop 0
	buffer_load_dwordx4 v146, s[0:3], s9 offen lds
	s_waitcnt vmcnt(8)
	s_waitcnt lgkmcnt(0)
	s_setprio 1
	s_barrier
	v_mfma_f32_16x16x32_bf16 v[28:31], v[6:9], v[10:13], v[66:69]
	v_mfma_f32_16x16x32_bf16 v[120:123], v[24:27], v[14:17], v[28:31]
	v_mfma_f32_16x16x32_bf16 v[28:31], v[228:231], v[10:13], v[70:73]
	v_mfma_f32_16x16x32_bf16 v[112:115], v[232:235], v[14:17], v[28:31]
	v_mfma_f32_16x16x32_bf16 v[28:31], v[6:9], v[32:35], v[74:77]
	v_mfma_f32_16x16x32_bf16 v[100:103], v[24:27], v[194:197], v[28:31]
	v_mfma_f32_16x16x32_bf16 v[28:31], v[228:231], v[32:35], v[78:81]
	v_mfma_f32_16x16x32_bf16 v[88:91], v[232:235], v[194:197], v[28:31]
	v_mfma_f32_16x16x32_bf16 v[28:31], v[6:9], v[208:211], v[82:85]
	v_mfma_f32_16x16x32_bf16 v[68:71], v[24:27], v[200:203], v[28:31]
	v_mfma_f32_16x16x32_bf16 v[28:31], v[228:231], v[208:211], v[92:95]
	v_mfma_f32_16x16x32_bf16 v[56:59], v[232:235], v[200:203], v[28:31]
	v_mfma_f32_16x16x32_bf16 v[28:31], v[6:9], v[204:207], v[96:99]
	v_mfma_f32_16x16x32_bf16 v[36:39], v[24:27], v[220:223], v[28:31]
	v_mfma_f32_16x16x32_bf16 v[28:31], v[228:231], v[204:207], v[104:107]
	v_mfma_f32_16x16x32_bf16 v[28:31], v[232:235], v[220:223], v[28:31]
	v_mfma_f32_16x16x32_bf16 v[64:67], v[236:239], v[10:13], v[108:111]
	v_mfma_f32_16x16x32_bf16 v[10:13], v[244:247], v[10:13], v[116:119]
	v_mfma_f32_16x16x32_bf16 v[124:127], v[150:153], v[14:17], v[10:13]
	v_mfma_f32_16x16x32_bf16 v[10:13], v[236:239], v[32:35], v[132:135]
	v_mfma_f32_16x16x32_bf16 v[116:119], v[240:243], v[194:197], v[10:13]
	v_mfma_f32_16x16x32_bf16 v[10:13], v[244:247], v[32:35], v[40:43]
	v_mfma_f32_16x16x32_bf16 v[108:111], v[150:153], v[194:197], v[10:13]
	v_mfma_f32_16x16x32_bf16 v[10:13], v[236:239], v[208:211], v[44:47]
	v_mfma_f32_16x16x32_bf16 v[92:95], v[240:243], v[200:203], v[10:13]
	v_mfma_f32_16x16x32_bf16 v[10:13], v[244:247], v[208:211], v[48:51]
	v_mfma_f32_16x16x32_bf16 v[80:83], v[150:153], v[200:203], v[10:13]
	v_mfma_f32_16x16x32_bf16 v[10:13], v[236:239], v[204:207], v[52:55]
	v_mfma_f32_16x16x32_bf16 v[128:131], v[240:243], v[14:17], v[64:67]
	v_mfma_f32_16x16x32_bf16 v[64:67], v[240:243], v[220:223], v[10:13]
	v_mfma_f32_16x16x32_bf16 v[10:13], v[244:247], v[204:207], v[60:63]
	v_mfma_f32_16x16x32_bf16 v[48:51], v[150:153], v[220:223], v[10:13]
	s_barrier
	s_setprio 0
	s_mov_b32 m0, s39
	s_or_b32 s9, s69, 0x180
	ds_read_b128 v[44:47], v149 offset:49152
	ds_read_b128 v[52:55], v149 offset:50176
	ds_read_b128 v[76:79], v149 offset:51200
	ds_read_b128 v[132:135], v149 offset:52224
	ds_read_b128 v[194:197], v149 offset:53248
	ds_read_b128 v[200:203], v149 offset:54272
	ds_read_b128 v[204:207], v149 offset:55296
	ds_read_b128 v[208:211], v149 offset:56320
	buffer_load_dwordx4 v145, s[4:7], s9 offen lds
	s_mov_b32 m0, s40
	s_nop 0
	buffer_load_dwordx4 v147, s[4:7], s9 offen lds
	s_or_b32 s9, s69, 0x40180
	s_mov_b32 m0, s43
	s_nop 0
	buffer_load_dwordx4 v145, s[4:7], s9 offen lds
	s_mov_b32 m0, s42
	s_nop 0
	buffer_load_dwordx4 v147, s[4:7], s9 offen lds
	s_waitcnt vmcnt(6)
	s_waitcnt lgkmcnt(0)
	s_nop 0
	s_setprio 1
	s_barrier
	v_mfma_f32_16x16x32_bf16 v[10:13], v[6:9], v[44:47], v[136:139]
	v_mfma_f32_16x16x32_bf16 v[72:75], v[24:27], v[52:55], v[10:13]
	v_mfma_f32_16x16x32_bf16 v[10:13], v[228:231], v[44:47], v[140:143]
	v_mfma_f32_16x16x32_bf16 v[60:63], v[232:235], v[52:55], v[10:13]
	v_mfma_f32_16x16x32_bf16 v[10:13], v[6:9], v[76:79], v[154:157]
	v_mfma_f32_16x16x32_bf16 v[40:43], v[24:27], v[132:135], v[10:13]
	v_mfma_f32_16x16x32_bf16 v[10:13], v[228:231], v[76:79], v[158:161]
	v_mfma_f32_16x16x32_bf16 v[32:35], v[232:235], v[132:135], v[10:13]
	v_mfma_f32_16x16x32_bf16 v[10:13], v[6:9], v[194:197], v[162:165]
	v_mfma_f32_16x16x32_bf16 v[16:19], v[24:27], v[200:203], v[10:13]
	v_mfma_f32_16x16x32_bf16 v[10:13], v[228:231], v[194:197], v[166:169]
	v_mfma_f32_16x16x32_bf16 v[2:5], v[6:9], v[204:207], v[2:5]
	v_mfma_f32_16x16x32_bf16 v[12:15], v[232:235], v[200:203], v[10:13]
	v_mfma_f32_16x16x32_bf16 v[8:11], v[24:27], v[208:211], v[2:5]
	v_mfma_f32_16x16x32_bf16 v[2:5], v[228:231], v[204:207], v[170:173]
	v_mfma_f32_16x16x32_bf16 v[4:7], v[232:235], v[208:211], v[2:5]
	v_mfma_f32_16x16x32_bf16 v[24:27], v[236:239], v[44:47], v[174:177]
	v_mfma_f32_16x16x32_bf16 v[96:99], v[240:243], v[52:55], v[24:27]
	v_mfma_f32_16x16x32_bf16 v[24:27], v[244:247], v[44:47], v[178:181]
	v_mfma_f32_16x16x32_bf16 v[104:107], v[150:153], v[52:55], v[24:27]
	v_mfma_f32_16x16x32_bf16 v[24:27], v[236:239], v[76:79], v[182:185]
	v_mfma_f32_16x16x32_bf16 v[84:87], v[240:243], v[132:135], v[24:27]
	v_mfma_f32_16x16x32_bf16 v[24:27], v[244:247], v[76:79], v[186:189]
	v_mfma_f32_16x16x32_bf16 v[76:79], v[150:153], v[132:135], v[24:27]
	v_mfma_f32_16x16x32_bf16 v[24:27], v[236:239], v[194:197], v[190:193]
	v_mfma_f32_16x16x32_bf16 v[52:55], v[240:243], v[200:203], v[24:27]
	v_mfma_f32_16x16x32_bf16 v[24:27], v[244:247], v[194:197], v[212:215]
	v_mfma_f32_16x16x32_bf16 v[20:23], v[236:239], v[204:207], v[20:23]
	v_mfma_f32_16x16x32_bf16 v[44:47], v[150:153], v[200:203], v[24:27]
	v_mfma_f32_16x16x32_bf16 v[24:27], v[240:243], v[208:211], v[20:23]
	v_mfma_f32_16x16x32_bf16 v[20:23], v[244:247], v[204:207], v[216:219]
	v_mfma_f32_16x16x32_bf16 v[20:23], v[150:153], v[208:211], v[20:23]
	s_barrier
	s_setprio 0
	s_mov_b64 s[8:9], 0
	v_mov_b64_e32 v[234:235], v[198:199]
	v_mov_b64_e32 v[236:237], v[226:227]
	v_mov_b32_e32 v198, v0
	v_mov_b32_e32 v226, v225
	v_mov_b64_e32 v[244:245], 0x100
	v_mov_b64_e32 v[246:247], 0xff
